# pooling mixer: per-wave LDS image of the 48 window rows (coalesced loads once) instead of one scattered row load per window step
# speedup vs baseline: 1.0839x; 1.0148x over previous
.LBB0_471:
	s_cmpk_gt_i32 s4, 0x1df
	s_mov_b64 s[0:1], -1
	s_cbranch_scc1 .LBB0_470
	s_cmpk_gt_i32 s4, 0x11f
	s_cbranch_scc0 .LBB0_478
	s_and_b32 s5, s4, 3
	s_cmpk_gt_u32 s4, 0x17f
	s_cbranch_scc0 .LBB0_492
	s_add_i32 s0, s4, 0xfffffe80
	s_lshr_b32 s1, s0, 2
	s_cmp_lt_u32 s0, 64
	v_mov_b32_e32 v0, v160
	s_cselect_b32 s0, s96, s95
	s_add_i32 s1, s1, s0
	v_ashrrev_i32_e32 v2, 1, v0
	v_and_b32_e32 v2, 0xffffffe0, v2
	v_and_b32_e32 v61, 31, v0
	v_lshl_add_u32 v2, s1, 7, v2
	v_or_b32_e32 v54, v2, v61
	v_bfe_u32 v60, v0, 5, 1
	s_lshl_b32 s6, s5, 6
	v_cmp_gt_i32_e32 vcc, s58, v54
	v_mov_b32_e32 v3, 0x400
	v_mov_b32_e32 v4, 0x100
	s_lshl_b32 s8, 2, s5
	v_lshl_or_b32 v33, v60, 3, s6
	v_cndmask_b32_e32 v72, v3, v4, vcc
	v_cndmask_b32_e32 v3, v205, v206, vcc
	s_lshr_b32 s7, s8, 1
	v_lshl_or_b32 v0, v33, 1, v207
	v_mov_b32_e32 v6, v1
	v_mov_b32_e32 v7, v1
	v_and_b32_e32 v73, v3, v2
	v_lshl_add_u64 v[16:17], s[36:37], 0, v[0:1]
	v_subrev_u32_e32 v32, s7, v54
	v_mov_b32_e32 v0, v1
	v_mov_b32_e32 v2, v1
	v_mov_b32_e32 v3, v1
	v_mov_b32_e32 v4, v1
	v_mov_b32_e32 v5, v1
	v_mov_b64_e32 v[14:15], v[6:7]
	s_mov_b32 s2, 0
	v_sub_u32_e32 v74, 0, v73
	v_sub_u32_e32 v36, v32, v73
	v_mov_b64_e32 v[12:13], v[4:5]
	v_mov_b64_e32 v[10:11], v[2:3]
	v_mov_b64_e32 v[8:9], v[0:1]
	s_mov_b64 s[100:101], exec
	v_and_b32_e32 v142, 7, v160
	v_bfe_u32 v143, v160, 3, 3
	v_sub_u32_e32 v144, v54, v61
	v_add_u32_e32 v144, v144, v143
	v_add_u32_e32 v144, -8, v144
	v_sub_u32_e32 v145, v144, v73
	v_lshlrev_b32_e32 v146, 12, v144
	v_lshl_add_u32 v146, v142, 4, v146
	s_lshl_b32 s98, s5, 7
	s_addk_i32 s98, 0xe00
	s_mov_b32 s99, 0xffff0000
	v_add_u32_e32 v146, s98, v146
	v_mov_b32_e32 v118, 0
	v_mov_b32_e32 v119, 0
	v_mov_b32_e32 v120, 0
	v_mov_b32_e32 v121, 0
	v_mov_b32_e32 v122, 0
	v_mov_b32_e32 v123, 0
	v_mov_b32_e32 v124, 0
	v_mov_b32_e32 v125, 0
	v_mov_b32_e32 v126, 0
	v_mov_b32_e32 v127, 0
	v_mov_b32_e32 v128, 0
	v_mov_b32_e32 v129, 0
	v_mov_b32_e32 v130, 0
	v_mov_b32_e32 v131, 0
	v_mov_b32_e32 v132, 0
	v_mov_b32_e32 v133, 0
	v_mov_b32_e32 v134, 0
	v_mov_b32_e32 v135, 0
	v_mov_b32_e32 v136, 0
	v_mov_b32_e32 v137, 0
	v_mov_b32_e32 v138, 0
	v_mov_b32_e32 v139, 0
	v_mov_b32_e32 v140, 0
	v_mov_b32_e32 v141, 0
	v_cmp_lt_u32_e32 vcc, v145, v72
	s_and_b64 exec, s[100:101], vcc
	global_load_dwordx4 v[118:121], v146, s[36:37]
	s_mov_b64 exec, s[100:101]
	v_add_u32_e32 v147, 8, v145
	v_add_u32_e32 v148, 0x8000, v146
	v_cmp_lt_u32_e32 vcc, v147, v72
	s_and_b64 exec, s[100:101], vcc
	global_load_dwordx4 v[122:125], v148, s[36:37]
	s_mov_b64 exec, s[100:101]
	v_add_u32_e32 v147, 16, v145
	v_add_u32_e32 v148, 0x10000, v146
	v_cmp_lt_u32_e32 vcc, v147, v72
	s_and_b64 exec, s[100:101], vcc
	global_load_dwordx4 v[126:129], v148, s[36:37]
	s_mov_b64 exec, s[100:101]
	v_add_u32_e32 v147, 24, v145
	v_add_u32_e32 v148, 0x18000, v146
	v_cmp_lt_u32_e32 vcc, v147, v72
	s_and_b64 exec, s[100:101], vcc
	global_load_dwordx4 v[130:133], v148, s[36:37]
	s_mov_b64 exec, s[100:101]
	v_add_u32_e32 v147, 32, v145
	v_add_u32_e32 v148, 0x20000, v146
	v_cmp_lt_u32_e32 vcc, v147, v72
	s_and_b64 exec, s[100:101], vcc
	global_load_dwordx4 v[134:137], v148, s[36:37]
	s_mov_b64 exec, s[100:101]
	v_add_u32_e32 v147, 40, v145
	v_add_u32_e32 v148, 0x28000, v146
	v_cmp_lt_u32_e32 vcc, v147, v72
	s_and_b64 exec, s[100:101], vcc
	global_load_dwordx4 v[138:141], v148, s[36:37]
	s_mov_b64 exec, s[100:101]
	v_lshrrev_b32_e32 v147, 6, v160
	v_mul_u32_u24_e32 v147, 0x1b00, v147
	v_mul_u32_u24_e32 v148, 0x90, v143
	v_add_u32_e32 v148, v148, v147
	v_lshl_add_u32 v148, v142, 4, v148
	v_add_u32_e32 v149, 8, v61
	v_subrev_u32_e32 v149, s7, v149
	v_mul_u32_u24_e32 v149, 0x90, v149
	v_add_u32_e32 v149, v149, v147
	v_lshl_add_u32 v158, v60, 4, v149
	s_waitcnt vmcnt(5)
	ds_write_b128 v148, v[118:121]
	s_waitcnt vmcnt(4)
	ds_write_b128 v148, v[122:125] offset:1152
	s_waitcnt vmcnt(3)
	ds_write_b128 v148, v[126:129] offset:2304
	s_waitcnt vmcnt(2)
	ds_write_b128 v148, v[130:133] offset:3456
	s_waitcnt vmcnt(1)
	ds_write_b128 v148, v[134:137] offset:4608
	s_waitcnt vmcnt(0)
	ds_write_b128 v148, v[138:141] offset:5760
	s_mov_b32 s98, 0
	v_mov_b32_e32 v159, v158
.Lpoolk0_top:
	ds_read_b128 v[118:121], v159
	ds_read_b128 v[122:125], v159 offset:144
	s_cmp_lt_u32 s8, 4
	s_cbranch_scc1 .Lpoolk0_two
	ds_read_b128 v[126:129], v159 offset:288
	ds_read_b128 v[130:133], v159 offset:432
	s_waitcnt lgkmcnt(0)
	v_lshlrev_b32_e32 v134, 16, v118
	v_and_b32_e32 v135, s99, v118
	v_lshlrev_b32_e32 v136, 16, v119
	v_and_b32_e32 v137, s99, v119
	v_lshlrev_b32_e32 v138, 16, v120
	v_and_b32_e32 v139, s99, v120
	v_lshlrev_b32_e32 v140, 16, v121
	v_and_b32_e32 v141, s99, v121
	v_pk_add_f32 v[14:15], v[14:15], v[140:141]
	v_pk_add_f32 v[12:13], v[12:13], v[138:139]
	v_pk_add_f32 v[10:11], v[10:11], v[136:137]
	v_pk_add_f32 v[8:9], v[8:9], v[134:135]
	v_lshlrev_b32_e32 v134, 16, v122
	v_and_b32_e32 v135, s99, v122
	v_lshlrev_b32_e32 v136, 16, v123
	v_and_b32_e32 v137, s99, v123
	v_lshlrev_b32_e32 v138, 16, v124
	v_and_b32_e32 v139, s99, v124
	v_lshlrev_b32_e32 v140, 16, v125
	v_and_b32_e32 v141, s99, v125
	v_pk_add_f32 v[14:15], v[14:15], v[140:141]
	v_pk_add_f32 v[12:13], v[12:13], v[138:139]
	v_pk_add_f32 v[10:11], v[10:11], v[136:137]
	v_pk_add_f32 v[8:9], v[8:9], v[134:135]
	v_lshlrev_b32_e32 v134, 16, v126
	v_and_b32_e32 v135, s99, v126
	v_lshlrev_b32_e32 v136, 16, v127
	v_and_b32_e32 v137, s99, v127
	v_lshlrev_b32_e32 v138, 16, v128
	v_and_b32_e32 v139, s99, v128
	v_lshlrev_b32_e32 v140, 16, v129
	v_and_b32_e32 v141, s99, v129
	v_pk_add_f32 v[14:15], v[14:15], v[140:141]
	v_pk_add_f32 v[12:13], v[12:13], v[138:139]
	v_pk_add_f32 v[10:11], v[10:11], v[136:137]
	v_pk_add_f32 v[8:9], v[8:9], v[134:135]
	v_lshlrev_b32_e32 v134, 16, v130
	v_and_b32_e32 v135, s99, v130
	v_lshlrev_b32_e32 v136, 16, v131
	v_and_b32_e32 v137, s99, v131
	v_lshlrev_b32_e32 v138, 16, v132
	v_and_b32_e32 v139, s99, v132
	v_lshlrev_b32_e32 v140, 16, v133
	v_and_b32_e32 v141, s99, v133
	v_pk_add_f32 v[14:15], v[14:15], v[140:141]
	v_pk_add_f32 v[12:13], v[12:13], v[138:139]
	v_pk_add_f32 v[10:11], v[10:11], v[136:137]
	v_pk_add_f32 v[8:9], v[8:9], v[134:135]
	v_add_u32_e32 v159, 576, v159
	s_add_i32 s98, s98, 4
	s_cmp_lt_u32 s98, s8
	s_cbranch_scc1 .Lpoolk0_top
	s_branch .Lpoolk0_done
.Lpoolk0_two:
	s_waitcnt lgkmcnt(0)
	v_lshlrev_b32_e32 v134, 16, v118
	v_and_b32_e32 v135, s99, v118
	v_lshlrev_b32_e32 v136, 16, v119
	v_and_b32_e32 v137, s99, v119
	v_lshlrev_b32_e32 v138, 16, v120
	v_and_b32_e32 v139, s99, v120
	v_lshlrev_b32_e32 v140, 16, v121
	v_and_b32_e32 v141, s99, v121
	v_pk_add_f32 v[14:15], v[14:15], v[140:141]
	v_pk_add_f32 v[12:13], v[12:13], v[138:139]
	v_pk_add_f32 v[10:11], v[10:11], v[136:137]
	v_pk_add_f32 v[8:9], v[8:9], v[134:135]
	v_lshlrev_b32_e32 v134, 16, v122
	v_and_b32_e32 v135, s99, v122
	v_lshlrev_b32_e32 v136, 16, v123
	v_and_b32_e32 v137, s99, v123
	v_lshlrev_b32_e32 v138, 16, v124
	v_and_b32_e32 v139, s99, v124
	v_lshlrev_b32_e32 v140, 16, v125
	v_and_b32_e32 v141, s99, v125
	v_pk_add_f32 v[14:15], v[14:15], v[140:141]
	v_pk_add_f32 v[12:13], v[12:13], v[138:139]
	v_pk_add_f32 v[10:11], v[10:11], v[136:137]
	v_pk_add_f32 v[8:9], v[8:9], v[134:135]
.Lpoolk0_done:
	s_branch .LBB0_479

.LBB0_479:
	s_mov_b64 s[24:25], s[72:73]
	s_mov_b64 s[26:27], s[74:75]
	v_ashrrev_i32_e32 v55, 31, v54
	v_readlane_b32 s68, v253, 19
	s_or_b32 s0, s5, s90
	v_lshlrev_b64 v[2:3], 12, v[54:55]
	v_readlane_b32 s72, v253, 23
	v_readlane_b32 s73, v253, 24
	s_lshl_b32 s0, s0, 14
	v_readlane_b32 s74, v253, 25
	v_readlane_b32 s75, v253, 26
	v_readlane_b32 s76, v253, 27
	v_readlane_b32 s77, v253, 28
	v_readlane_b32 s78, v253, 29
	v_readlane_b32 s79, v253, 30
	s_mov_b64 s[40:41], s[72:73]
	v_lshl_add_u64 v[2:3], s[36:37], 0, v[2:3]
	v_lshlrev_b32_e32 v0, 1, v33
	v_lshlrev_b32_e32 v63, 9, v60
	s_add_u32 s0, s40, s0
	v_lshl_add_u64 v[56:57], v[2:3], 0, v[0:1]
	v_or_b32_e32 v2, v63, v61
	v_or_b32_e32 v62, 32, v61
	s_addc_u32 s1, s41, 0
	v_lshlrev_b32_e32 v2, 2, v2
	v_or_b32_e32 v3, v63, v62
	global_load_dwordx4 v[42:45], v[56:57], off offset:3584
	global_load_dword v64, v2, s[0:1]
	global_load_dword v65, v2, s[0:1] offset:256
	global_load_dword v66, v2, s[0:1] offset:512
	global_load_dword v67, v2, s[0:1] offset:768
	global_load_dword v68, v2, s[0:1] offset:1024
	global_load_dword v69, v2, s[0:1] offset:1280
	global_load_dword v70, v2, s[0:1] offset:1536
	global_load_dword v83, v2, s[0:1] offset:128
	v_lshlrev_b32_e32 v3, 2, v3
	global_load_dword v71, v2, s[0:1] offset:1792
	global_load_dword v84, v3, s[0:1] offset:256
	global_load_dword v85, v3, s[0:1] offset:512
	global_load_dword v86, v3, s[0:1] offset:768
	global_load_dword v87, v3, s[0:1] offset:1024
	global_load_dword v88, v3, s[0:1] offset:1280
	global_load_dword v89, v3, s[0:1] offset:1536
	global_load_dword v90, v3, s[0:1] offset:1792
	v_or_b32_e32 v0, 0xe20, v0
	v_mov_b32_e32 v6, v1
	v_mov_b32_e32 v7, v1
	v_lshl_add_u64 v[24:25], s[36:37], 0, v[0:1]
	v_mov_b32_e32 v0, v1
	v_mov_b32_e32 v2, v1
	v_mov_b32_e32 v3, v1
	v_mov_b32_e32 v4, v1
	v_mov_b32_e32 v5, v1
	v_mov_b64_e32 v[22:23], v[6:7]
	s_mov_b32 s9, 0
	v_mov_b64_e32 v[20:21], v[4:5]
	v_mov_b64_e32 v[18:19], v[2:3]
	v_mov_b64_e32 v[16:17], v[0:1]
	v_readlane_b32 s69, v253, 20
	v_readlane_b32 s70, v253, 21
	v_readlane_b32 s71, v253, 22
	v_readlane_b32 s80, v253, 31
	v_readlane_b32 s81, v253, 32
	v_readlane_b32 s82, v253, 33
	v_readlane_b32 s83, v253, 34
	s_mov_b64 s[42:43], s[74:75]
	s_mov_b64 s[44:45], s[76:77]
	s_mov_b64 s[46:47], s[78:79]
	s_mov_b32 s98, 0
	v_mov_b32_e32 v159, v158
.Lpoolk1_top:
	ds_read_b128 v[118:121], v159 offset:32
	ds_read_b128 v[122:125], v159 offset:176
	s_cmp_lt_u32 s8, 4
	s_cbranch_scc1 .Lpoolk1_two
	ds_read_b128 v[126:129], v159 offset:320
	ds_read_b128 v[130:133], v159 offset:464
	s_waitcnt lgkmcnt(0)
	v_lshlrev_b32_e32 v134, 16, v118
	v_and_b32_e32 v135, s99, v118
	v_lshlrev_b32_e32 v136, 16, v119
	v_and_b32_e32 v137, s99, v119
	v_lshlrev_b32_e32 v138, 16, v120
	v_and_b32_e32 v139, s99, v120
	v_lshlrev_b32_e32 v140, 16, v121
	v_and_b32_e32 v141, s99, v121
	v_pk_add_f32 v[22:23], v[22:23], v[140:141]
	v_pk_add_f32 v[20:21], v[20:21], v[138:139]
	v_pk_add_f32 v[18:19], v[18:19], v[136:137]
	v_pk_add_f32 v[16:17], v[16:17], v[134:135]
	v_lshlrev_b32_e32 v134, 16, v122
	v_and_b32_e32 v135, s99, v122
	v_lshlrev_b32_e32 v136, 16, v123
	v_and_b32_e32 v137, s99, v123
	v_lshlrev_b32_e32 v138, 16, v124
	v_and_b32_e32 v139, s99, v124
	v_lshlrev_b32_e32 v140, 16, v125
	v_and_b32_e32 v141, s99, v125
	v_pk_add_f32 v[22:23], v[22:23], v[140:141]
	v_pk_add_f32 v[20:21], v[20:21], v[138:139]
	v_pk_add_f32 v[18:19], v[18:19], v[136:137]
	v_pk_add_f32 v[16:17], v[16:17], v[134:135]
	v_lshlrev_b32_e32 v134, 16, v126
	v_and_b32_e32 v135, s99, v126
	v_lshlrev_b32_e32 v136, 16, v127
	v_and_b32_e32 v137, s99, v127
	v_lshlrev_b32_e32 v138, 16, v128
	v_and_b32_e32 v139, s99, v128
	v_lshlrev_b32_e32 v140, 16, v129
	v_and_b32_e32 v141, s99, v129
	v_pk_add_f32 v[22:23], v[22:23], v[140:141]
	v_pk_add_f32 v[20:21], v[20:21], v[138:139]
	v_pk_add_f32 v[18:19], v[18:19], v[136:137]
	v_pk_add_f32 v[16:17], v[16:17], v[134:135]
	v_lshlrev_b32_e32 v134, 16, v130
	v_and_b32_e32 v135, s99, v130
	v_lshlrev_b32_e32 v136, 16, v131
	v_and_b32_e32 v137, s99, v131
	v_lshlrev_b32_e32 v138, 16, v132
	v_and_b32_e32 v139, s99, v132
	v_lshlrev_b32_e32 v140, 16, v133
	v_and_b32_e32 v141, s99, v133
	v_pk_add_f32 v[22:23], v[22:23], v[140:141]
	v_pk_add_f32 v[20:21], v[20:21], v[138:139]
	v_pk_add_f32 v[18:19], v[18:19], v[136:137]
	v_pk_add_f32 v[16:17], v[16:17], v[134:135]
	v_add_u32_e32 v159, 576, v159
	s_add_i32 s98, s98, 4
	s_cmp_lt_u32 s98, s8
	s_cbranch_scc1 .Lpoolk1_top
	s_branch .Lpoolk1_done
.Lpoolk1_two:
	s_waitcnt lgkmcnt(0)
	v_lshlrev_b32_e32 v134, 16, v118
	v_and_b32_e32 v135, s99, v118
	v_lshlrev_b32_e32 v136, 16, v119
	v_and_b32_e32 v137, s99, v119
	v_lshlrev_b32_e32 v138, 16, v120
	v_and_b32_e32 v139, s99, v120
	v_lshlrev_b32_e32 v140, 16, v121
	v_and_b32_e32 v141, s99, v121
	v_pk_add_f32 v[22:23], v[22:23], v[140:141]
	v_pk_add_f32 v[20:21], v[20:21], v[138:139]
	v_pk_add_f32 v[18:19], v[18:19], v[136:137]
	v_pk_add_f32 v[16:17], v[16:17], v[134:135]
	v_lshlrev_b32_e32 v134, 16, v122
	v_and_b32_e32 v135, s99, v122
	v_lshlrev_b32_e32 v136, 16, v123
	v_and_b32_e32 v137, s99, v123
	v_lshlrev_b32_e32 v138, 16, v124
	v_and_b32_e32 v139, s99, v124
	v_lshlrev_b32_e32 v140, 16, v125
	v_and_b32_e32 v141, s99, v125
	v_pk_add_f32 v[22:23], v[22:23], v[140:141]
	v_pk_add_f32 v[20:21], v[20:21], v[138:139]
	v_pk_add_f32 v[18:19], v[18:19], v[136:137]
	v_pk_add_f32 v[16:17], v[16:17], v[134:135]
.Lpoolk1_done:
.LBB0_483:
	v_or_b32_e32 v0, 0x400, v63
	v_or_b32_e32 v3, 0x440, v63
	v_or_b32_e32 v5, 0x480, v63
	v_or_b32_e32 v7, 0x4c0, v63
	v_or_b32_e32 v2, v0, v61
	v_or_b32_e32 v4, v3, v61
	v_or_b32_e32 v6, v5, v61
	v_or_b32_e32 v24, v7, v61
	v_or_b32_e32 v25, 0x500, v63
	v_or_b32_e32 v27, 0x540, v63
	v_or_b32_e32 v29, 0x580, v63
	v_or_b32_e32 v31, 0x5c0, v63
	v_lshlrev_b32_e32 v2, 2, v2
	v_lshlrev_b32_e32 v4, 2, v4
	v_lshlrev_b32_e32 v6, 2, v6
	v_lshlrev_b32_e32 v24, 2, v24
	v_or_b32_e32 v26, v25, v61
	v_or_b32_e32 v28, v27, v61
	v_or_b32_e32 v30, v29, v61
	v_or_b32_e32 v34, v31, v61
	v_or_b32_e32 v0, v0, v62
	global_load_dwordx4 v[46:49], v[56:57], off offset:3616
	v_lshlrev_b32_e32 v26, 2, v26
	v_lshlrev_b32_e32 v28, 2, v28
	v_lshlrev_b32_e32 v30, 2, v30
	v_lshlrev_b32_e32 v34, 2, v34
	global_load_dword v91, v2, s[0:1]
	global_load_dword v92, v4, s[0:1]
	global_load_dword v93, v6, s[0:1]
	global_load_dword v94, v24, s[0:1]
	global_load_dword v95, v26, s[0:1]
	global_load_dword v96, v28, s[0:1]
	global_load_dword v97, v30, s[0:1]
	global_load_dword v98, v34, s[0:1]
	v_lshlrev_b32_e32 v0, 2, v0
	v_or_b32_e32 v2, v3, v62
	v_or_b32_e32 v3, v5, v62
	v_or_b32_e32 v4, v7, v62
	v_or_b32_e32 v5, v25, v62
	v_or_b32_e32 v6, v27, v62
	v_or_b32_e32 v7, v29, v62
	v_or_b32_e32 v24, v31, v62
	v_lshlrev_b32_e32 v2, 2, v2
	v_lshlrev_b32_e32 v3, 2, v3
	v_lshlrev_b32_e32 v4, 2, v4
	v_lshlrev_b32_e32 v5, 2, v5
	v_lshlrev_b32_e32 v6, 2, v6
	v_lshlrev_b32_e32 v7, 2, v7
	v_lshlrev_b32_e32 v24, 2, v24
	global_load_dword v75, v0, s[0:1]
	global_load_dword v76, v2, s[0:1]
	global_load_dword v77, v3, s[0:1]
	global_load_dword v78, v4, s[0:1]
	global_load_dword v79, v5, s[0:1]
	global_load_dword v80, v6, s[0:1]
	global_load_dword v81, v7, s[0:1]
	global_load_dword v82, v24, s[0:1]
	v_lshl_or_b32 v0, v33, 1, v208
	v_mov_b32_e32 v6, v1
	v_mov_b32_e32 v7, v1
	v_lshl_add_u64 v[34:35], s[36:37], 0, v[0:1]
	v_mov_b32_e32 v0, v1
	v_mov_b32_e32 v2, v1
	v_mov_b32_e32 v3, v1
	v_mov_b32_e32 v4, v1
	v_mov_b32_e32 v5, v1
	v_mov_b64_e32 v[30:31], v[6:7]
	s_mov_b32 s9, 0
	v_mov_b64_e32 v[28:29], v[4:5]
	v_mov_b64_e32 v[26:27], v[2:3]
	v_mov_b64_e32 v[24:25], v[0:1]
	s_mov_b32 s98, 0
	v_mov_b32_e32 v159, v158
.Lpoolk2_top:
	ds_read_b128 v[118:121], v159 offset:64
	ds_read_b128 v[122:125], v159 offset:208
	s_cmp_lt_u32 s8, 4
	s_cbranch_scc1 .Lpoolk2_two
	ds_read_b128 v[126:129], v159 offset:352
	ds_read_b128 v[130:133], v159 offset:496
	s_waitcnt lgkmcnt(0)
	v_lshlrev_b32_e32 v134, 16, v118
	v_and_b32_e32 v135, s99, v118
	v_lshlrev_b32_e32 v136, 16, v119
	v_and_b32_e32 v137, s99, v119
	v_lshlrev_b32_e32 v138, 16, v120
	v_and_b32_e32 v139, s99, v120
	v_lshlrev_b32_e32 v140, 16, v121
	v_and_b32_e32 v141, s99, v121
	v_pk_add_f32 v[30:31], v[30:31], v[140:141]
	v_pk_add_f32 v[28:29], v[28:29], v[138:139]
	v_pk_add_f32 v[26:27], v[26:27], v[136:137]
	v_pk_add_f32 v[24:25], v[24:25], v[134:135]
	v_lshlrev_b32_e32 v134, 16, v122
	v_and_b32_e32 v135, s99, v122
	v_lshlrev_b32_e32 v136, 16, v123
	v_and_b32_e32 v137, s99, v123
	v_lshlrev_b32_e32 v138, 16, v124
	v_and_b32_e32 v139, s99, v124
	v_lshlrev_b32_e32 v140, 16, v125
	v_and_b32_e32 v141, s99, v125
	v_pk_add_f32 v[30:31], v[30:31], v[140:141]
	v_pk_add_f32 v[28:29], v[28:29], v[138:139]
	v_pk_add_f32 v[26:27], v[26:27], v[136:137]
	v_pk_add_f32 v[24:25], v[24:25], v[134:135]
	v_lshlrev_b32_e32 v134, 16, v126
	v_and_b32_e32 v135, s99, v126
	v_lshlrev_b32_e32 v136, 16, v127
	v_and_b32_e32 v137, s99, v127
	v_lshlrev_b32_e32 v138, 16, v128
	v_and_b32_e32 v139, s99, v128
	v_lshlrev_b32_e32 v140, 16, v129
	v_and_b32_e32 v141, s99, v129
	v_pk_add_f32 v[30:31], v[30:31], v[140:141]
	v_pk_add_f32 v[28:29], v[28:29], v[138:139]
	v_pk_add_f32 v[26:27], v[26:27], v[136:137]
	v_pk_add_f32 v[24:25], v[24:25], v[134:135]
	v_lshlrev_b32_e32 v134, 16, v130
	v_and_b32_e32 v135, s99, v130
	v_lshlrev_b32_e32 v136, 16, v131
	v_and_b32_e32 v137, s99, v131
	v_lshlrev_b32_e32 v138, 16, v132
	v_and_b32_e32 v139, s99, v132
	v_lshlrev_b32_e32 v140, 16, v133
	v_and_b32_e32 v141, s99, v133
	v_pk_add_f32 v[30:31], v[30:31], v[140:141]
	v_pk_add_f32 v[28:29], v[28:29], v[138:139]
	v_pk_add_f32 v[26:27], v[26:27], v[136:137]
	v_pk_add_f32 v[24:25], v[24:25], v[134:135]
	v_add_u32_e32 v159, 576, v159
	s_add_i32 s98, s98, 4
	s_cmp_lt_u32 s98, s8
	s_cbranch_scc1 .Lpoolk2_top
	s_branch .Lpoolk2_done
.Lpoolk2_two:
	s_waitcnt lgkmcnt(0)
	v_lshlrev_b32_e32 v134, 16, v118
	v_and_b32_e32 v135, s99, v118
	v_lshlrev_b32_e32 v136, 16, v119
	v_and_b32_e32 v137, s99, v119
	v_lshlrev_b32_e32 v138, 16, v120
	v_and_b32_e32 v139, s99, v120
	v_lshlrev_b32_e32 v140, 16, v121
	v_and_b32_e32 v141, s99, v121
	v_pk_add_f32 v[30:31], v[30:31], v[140:141]
	v_pk_add_f32 v[28:29], v[28:29], v[138:139]
	v_pk_add_f32 v[26:27], v[26:27], v[136:137]
	v_pk_add_f32 v[24:25], v[24:25], v[134:135]
	v_lshlrev_b32_e32 v134, 16, v122
	v_and_b32_e32 v135, s99, v122
	v_lshlrev_b32_e32 v136, 16, v123
	v_and_b32_e32 v137, s99, v123
	v_lshlrev_b32_e32 v138, 16, v124
	v_and_b32_e32 v139, s99, v124
	v_lshlrev_b32_e32 v140, 16, v125
	v_and_b32_e32 v141, s99, v125
	v_pk_add_f32 v[30:31], v[30:31], v[140:141]
	v_pk_add_f32 v[28:29], v[28:29], v[138:139]
	v_pk_add_f32 v[26:27], v[26:27], v[136:137]
	v_pk_add_f32 v[24:25], v[24:25], v[134:135]
.Lpoolk2_done:
.LBB0_487:
	v_or_b32_e32 v0, 0x800, v63
	v_or_b32_e32 v3, 0x840, v63
	v_or_b32_e32 v5, 0x880, v63
	v_or_b32_e32 v7, 0x8c0, v63
	v_or_b32_e32 v2, v0, v61
	v_or_b32_e32 v4, v3, v61
	v_or_b32_e32 v6, v5, v61
	v_or_b32_e32 v34, v7, v61
	v_or_b32_e32 v35, 0x900, v63
	v_or_b32_e32 v37, 0x940, v63
	v_or_b32_e32 v39, 0x980, v63
	v_or_b32_e32 v41, 0x9c0, v63
	v_lshlrev_b32_e32 v2, 2, v2
	v_lshlrev_b32_e32 v4, 2, v4
	v_lshlrev_b32_e32 v6, 2, v6
	v_lshlrev_b32_e32 v34, 2, v34
	v_or_b32_e32 v36, v35, v61
	v_or_b32_e32 v38, v37, v61
	v_or_b32_e32 v40, v39, v61
	v_or_b32_e32 v58, v41, v61
	v_or_b32_e32 v0, v0, v62
	global_load_dwordx4 v[50:53], v[56:57], off offset:3648
	v_lshlrev_b32_e32 v36, 2, v36
	v_lshlrev_b32_e32 v38, 2, v38
	v_lshlrev_b32_e32 v40, 2, v40
	v_lshlrev_b32_e32 v58, 2, v58
	global_load_dword v99, v2, s[0:1]
	global_load_dword v100, v4, s[0:1]
	global_load_dword v101, v6, s[0:1]
	global_load_dword v102, v34, s[0:1]
	global_load_dword v103, v36, s[0:1]
	global_load_dword v104, v38, s[0:1]
	global_load_dword v105, v40, s[0:1]
	global_load_dword v106, v58, s[0:1]
	v_lshlrev_b32_e32 v0, 2, v0
	v_or_b32_e32 v2, v3, v62
	v_or_b32_e32 v3, v5, v62
	v_or_b32_e32 v4, v7, v62
	v_or_b32_e32 v5, v35, v62
	v_or_b32_e32 v6, v37, v62
	v_or_b32_e32 v7, v39, v62
	v_or_b32_e32 v34, v41, v62
	v_lshlrev_b32_e32 v2, 2, v2
	v_lshlrev_b32_e32 v3, 2, v3
	v_lshlrev_b32_e32 v4, 2, v4
	v_lshlrev_b32_e32 v5, 2, v5
	v_lshlrev_b32_e32 v6, 2, v6
	v_lshlrev_b32_e32 v7, 2, v7
	v_lshlrev_b32_e32 v34, 2, v34
	global_load_dword v107, v0, s[0:1]
	global_load_dword v108, v2, s[0:1]
	global_load_dword v109, v3, s[0:1]
	global_load_dword v110, v4, s[0:1]
	global_load_dword v111, v5, s[0:1]
	global_load_dword v112, v6, s[0:1]
	global_load_dword v113, v7, s[0:1]
	global_load_dword v114, v34, s[0:1]
	v_lshl_or_b32 v0, v33, 1, v209
	v_mov_b32_e32 v6, v1
	v_mov_b32_e32 v7, v1
	v_lshl_add_u64 v[58:59], s[36:37], 0, v[0:1]
	v_mov_b32_e32 v0, v1
	v_mov_b32_e32 v2, v1
	v_mov_b32_e32 v3, v1
	v_mov_b32_e32 v4, v1
	v_mov_b32_e32 v5, v1
	v_mov_b64_e32 v[40:41], v[6:7]
	v_mov_b64_e32 v[38:39], v[4:5]
	v_mov_b64_e32 v[36:37], v[2:3]
	v_mov_b64_e32 v[34:35], v[0:1]
	s_mov_b32 s98, 0
	v_mov_b32_e32 v159, v158
.Lpoolk3_top:
	ds_read_b128 v[118:121], v159 offset:96
	ds_read_b128 v[122:125], v159 offset:240
	s_cmp_lt_u32 s8, 4
	s_cbranch_scc1 .Lpoolk3_two
	ds_read_b128 v[126:129], v159 offset:384
	ds_read_b128 v[130:133], v159 offset:528
	s_waitcnt lgkmcnt(0)
	v_lshlrev_b32_e32 v134, 16, v118
	v_and_b32_e32 v135, s99, v118
	v_lshlrev_b32_e32 v136, 16, v119
	v_and_b32_e32 v137, s99, v119
	v_lshlrev_b32_e32 v138, 16, v120
	v_and_b32_e32 v139, s99, v120
	v_lshlrev_b32_e32 v140, 16, v121
	v_and_b32_e32 v141, s99, v121
	v_pk_add_f32 v[40:41], v[40:41], v[140:141]
	v_pk_add_f32 v[38:39], v[38:39], v[138:139]
	v_pk_add_f32 v[36:37], v[36:37], v[136:137]
	v_pk_add_f32 v[34:35], v[34:35], v[134:135]
	v_lshlrev_b32_e32 v134, 16, v122
	v_and_b32_e32 v135, s99, v122
	v_lshlrev_b32_e32 v136, 16, v123
	v_and_b32_e32 v137, s99, v123
	v_lshlrev_b32_e32 v138, 16, v124
	v_and_b32_e32 v139, s99, v124
	v_lshlrev_b32_e32 v140, 16, v125
	v_and_b32_e32 v141, s99, v125
	v_pk_add_f32 v[40:41], v[40:41], v[140:141]
	v_pk_add_f32 v[38:39], v[38:39], v[138:139]
	v_pk_add_f32 v[36:37], v[36:37], v[136:137]
	v_pk_add_f32 v[34:35], v[34:35], v[134:135]
	v_lshlrev_b32_e32 v134, 16, v126
	v_and_b32_e32 v135, s99, v126
	v_lshlrev_b32_e32 v136, 16, v127
	v_and_b32_e32 v137, s99, v127
	v_lshlrev_b32_e32 v138, 16, v128
	v_and_b32_e32 v139, s99, v128
	v_lshlrev_b32_e32 v140, 16, v129
	v_and_b32_e32 v141, s99, v129
	v_pk_add_f32 v[40:41], v[40:41], v[140:141]
	v_pk_add_f32 v[38:39], v[38:39], v[138:139]
	v_pk_add_f32 v[36:37], v[36:37], v[136:137]
	v_pk_add_f32 v[34:35], v[34:35], v[134:135]
	v_lshlrev_b32_e32 v134, 16, v130
	v_and_b32_e32 v135, s99, v130
	v_lshlrev_b32_e32 v136, 16, v131
	v_and_b32_e32 v137, s99, v131
	v_lshlrev_b32_e32 v138, 16, v132
	v_and_b32_e32 v139, s99, v132
	v_lshlrev_b32_e32 v140, 16, v133
	v_and_b32_e32 v141, s99, v133
	v_pk_add_f32 v[40:41], v[40:41], v[140:141]
	v_pk_add_f32 v[38:39], v[38:39], v[138:139]
	v_pk_add_f32 v[36:37], v[36:37], v[136:137]
	v_pk_add_f32 v[34:35], v[34:35], v[134:135]
	v_add_u32_e32 v159, 576, v159
	s_add_i32 s98, s98, 4
	s_cmp_lt_u32 s98, s8
	s_cbranch_scc1 .Lpoolk3_top
	s_branch .Lpoolk3_done
.Lpoolk3_two:
	s_waitcnt lgkmcnt(0)
	v_lshlrev_b32_e32 v134, 16, v118
	v_and_b32_e32 v135, s99, v118
	v_lshlrev_b32_e32 v136, 16, v119
	v_and_b32_e32 v137, s99, v119
	v_lshlrev_b32_e32 v138, 16, v120
	v_and_b32_e32 v139, s99, v120
	v_lshlrev_b32_e32 v140, 16, v121
	v_and_b32_e32 v141, s99, v121
	v_pk_add_f32 v[40:41], v[40:41], v[140:141]
	v_pk_add_f32 v[38:39], v[38:39], v[138:139]
	v_pk_add_f32 v[36:37], v[36:37], v[136:137]
	v_pk_add_f32 v[34:35], v[34:35], v[134:135]
	v_lshlrev_b32_e32 v134, 16, v122
	v_and_b32_e32 v135, s99, v122
	v_lshlrev_b32_e32 v136, 16, v123
	v_and_b32_e32 v137, s99, v123
	v_lshlrev_b32_e32 v138, 16, v124
	v_and_b32_e32 v139, s99, v124
	v_lshlrev_b32_e32 v140, 16, v125
	v_and_b32_e32 v141, s99, v125
	v_pk_add_f32 v[40:41], v[40:41], v[140:141]
	v_pk_add_f32 v[38:39], v[38:39], v[138:139]
	v_pk_add_f32 v[36:37], v[36:37], v[136:137]
	v_pk_add_f32 v[34:35], v[34:35], v[134:135]
.Lpoolk3_done:
.LBB0_491:
	v_sub_u32_e32 v0, v54, v73
	v_subrev_u32_e32 v2, s7, v0
	v_add_u32_e32 v0, s7, v0
	v_max_i32_e32 v2, 0, v2
	v_min_i32_e32 v0, v0, v72
	v_sub_u32_e32 v0, v0, v2
	v_cvt_f32_i32_e32 v0, v0
	s_waitcnt vmcnt(33)
	v_and_b32_e32 v7, 0xffff0000, v48
	v_lshlrev_b32_e32 v32, 16, v49
	v_and_b32_e32 v33, 0xffff0000, v49
	v_div_scale_f32 v2, s[2:3], v0, v0, 1.0
	v_rcp_f32_e32 v3, v2
	v_cvt_pk_bf16_f32 v84, v83, v84
	v_cvt_pk_bf16_f32 v85, v85, v86
	v_cvt_pk_bf16_f32 v86, v87, v88
	v_fma_f32 v4, -v2, v3, 1.0
	v_fmac_f32_e32 v3, v4, v3
	v_div_scale_f32 v4, vcc, 1.0, v0, 1.0
	v_mul_f32_e32 v5, v4, v3
	v_fma_f32 v6, -v2, v5, v4
	v_fmac_f32_e32 v5, v6, v3
	v_fma_f32 v2, -v2, v5, v4
	v_div_fmas_f32 v2, v2, v3, v5
	v_div_fixup_f32 v0, v2, v0, 1.0
	v_lshlrev_b32_e32 v2, 16, v46
	v_and_b32_e32 v3, 0xffff0000, v46
	v_lshlrev_b32_e32 v6, 16, v48
	v_lshlrev_b32_e32 v4, 16, v47
	v_and_b32_e32 v5, 0xffff0000, v47
	v_pk_fma_f32 v[2:3], v[0:1], v[16:17], v[2:3] op_sel_hi:[0,1,1] neg_lo:[0,0,1] neg_hi:[0,0,1]
	v_pk_fma_f32 v[6:7], v[0:1], v[20:21], v[6:7] op_sel_hi:[0,1,1] neg_lo:[0,0,1] neg_hi:[0,0,1]
	v_pk_fma_f32 v[16:17], v[0:1], v[22:23], v[32:33] op_sel_hi:[0,1,1] neg_lo:[0,0,1] neg_hi:[0,0,1]
	v_pk_fma_f32 v[4:5], v[0:1], v[18:19], v[4:5] op_sel_hi:[0,1,1] neg_lo:[0,0,1] neg_hi:[0,0,1]
	v_cvt_pk_bf16_f32 v48, v6, v7
	v_cvt_pk_bf16_f32 v49, v16, v17
	s_waitcnt vmcnt(16)
	v_lshlrev_b32_e32 v6, 16, v50
	v_and_b32_e32 v7, 0xffff0000, v50
	v_lshlrev_b32_e32 v16, 16, v51
	v_and_b32_e32 v17, 0xffff0000, v51
	v_lshlrev_b32_e32 v18, 16, v52
	v_and_b32_e32 v19, 0xffff0000, v52
	v_lshlrev_b32_e32 v20, 16, v53
	v_and_b32_e32 v21, 0xffff0000, v53
	v_pk_fma_f32 v[6:7], v[0:1], v[24:25], v[6:7] op_sel_hi:[0,1,1] neg_lo:[0,0,1] neg_hi:[0,0,1]
	v_pk_fma_f32 v[16:17], v[0:1], v[26:27], v[16:17] op_sel_hi:[0,1,1] neg_lo:[0,0,1] neg_hi:[0,0,1]
	v_pk_fma_f32 v[18:19], v[0:1], v[28:29], v[18:19] op_sel_hi:[0,1,1] neg_lo:[0,0,1] neg_hi:[0,0,1]
	v_pk_fma_f32 v[20:21], v[0:1], v[30:31], v[20:21] op_sel_hi:[0,1,1] neg_lo:[0,0,1] neg_hi:[0,0,1]
	v_cvt_pk_bf16_f32 v50, v6, v7
	v_cvt_pk_bf16_f32 v51, v16, v17
	v_cvt_pk_bf16_f32 v52, v18, v19
	v_cvt_pk_bf16_f32 v53, v20, v21
	v_lshlrev_b32_e32 v6, 16, v42
	v_and_b32_e32 v7, 0xffff0000, v42
	v_lshlrev_b32_e32 v16, 16, v43
	v_and_b32_e32 v17, 0xffff0000, v43
	v_lshlrev_b32_e32 v18, 16, v44
	v_and_b32_e32 v19, 0xffff0000, v44
	v_lshlrev_b32_e32 v20, 16, v45
	v_and_b32_e32 v21, 0xffff0000, v45
	v_pk_fma_f32 v[6:7], v[0:1], v[8:9], v[6:7] op_sel_hi:[0,1,1] neg_lo:[0,0,1] neg_hi:[0,0,1]
	v_pk_fma_f32 v[8:9], v[0:1], v[10:11], v[16:17] op_sel_hi:[0,1,1] neg_lo:[0,0,1] neg_hi:[0,0,1]
	v_pk_fma_f32 v[10:11], v[0:1], v[12:13], v[18:19] op_sel_hi:[0,1,1] neg_lo:[0,0,1] neg_hi:[0,0,1]
	v_pk_fma_f32 v[12:13], v[0:1], v[14:15], v[20:21] op_sel_hi:[0,1,1] neg_lo:[0,0,1] neg_hi:[0,0,1]
	v_cvt_pk_bf16_f32 v6, v6, v7
	v_cvt_pk_bf16_f32 v7, v8, v9
	v_cvt_pk_bf16_f32 v8, v10, v11
	v_cvt_pk_bf16_f32 v9, v12, v13
	v_cvt_pk_bf16_f32 v10, v64, v65
	v_cvt_pk_bf16_f32 v11, v66, v67
	v_cvt_pk_bf16_f32 v12, v68, v69
	v_cvt_pk_bf16_f32 v13, v70, v71
	v_cvt_pk_bf16_f32 v46, v2, v3
	v_cvt_pk_bf16_f32 v47, v4, v5
	v_mfma_f32_32x32x16_bf16 v[18:33], v[10:13], v[6:9], 0
	v_cvt_pk_bf16_f32 v2, v91, v92
	v_cvt_pk_bf16_f32 v3, v93, v94
	v_cvt_pk_bf16_f32 v4, v95, v96
	v_cvt_pk_bf16_f32 v5, v97, v98
	v_cvt_pk_bf16_f32 v87, v89, v90
	v_cvt_pk_bf16_f32 v42, v75, v76
	v_cvt_pk_bf16_f32 v43, v77, v78
	v_mfma_f32_32x32x16_bf16 v[18:33], v[2:5], v[46:49], v[18:33]
	v_cvt_pk_bf16_f32 v44, v79, v80
	v_cvt_pk_bf16_f32 v45, v81, v82
	s_waitcnt vmcnt(14)
	v_cvt_pk_bf16_f32 v88, v99, v100
	s_waitcnt vmcnt(12)
	v_cvt_pk_bf16_f32 v89, v101, v102
	s_waitcnt vmcnt(10)
	v_cvt_pk_bf16_f32 v90, v103, v104
	s_waitcnt vmcnt(8)
	v_cvt_pk_bf16_f32 v91, v105, v106
	s_waitcnt vmcnt(6)
	v_cvt_pk_bf16_f32 v92, v107, v108
	v_mfma_f32_32x32x16_bf16 v[2:17], v[84:87], v[6:9], 0
	s_waitcnt vmcnt(4)
	v_cvt_pk_bf16_f32 v93, v109, v110
	s_waitcnt vmcnt(2)
	v_cvt_pk_bf16_f32 v94, v111, v112
	s_waitcnt vmcnt(0)
	v_cvt_pk_bf16_f32 v95, v113, v114
	v_readlane_b32 s68, v253, 19
	v_readlane_b32 s74, v253, 25
	v_readlane_b32 s75, v253, 26
	v_readlane_b32 s72, v253, 23
	v_mfma_f32_32x32x16_bf16 v[2:17], v[42:45], v[46:49], v[2:17]
	global_load_dwordx4 v[42:45], v[56:57], off offset:3680
	v_readlane_b32 s73, v253, 24
	s_lshl_b32 s20, s6, 1
	v_readlane_b32 s80, v253, 31
	v_readlane_b32 s81, v253, 32
	v_readlane_b32 s82, v253, 33
	v_readlane_b32 s83, v253, 34
	v_mfma_f32_32x32x16_bf16 v[18:33], v[88:91], v[50:53], v[18:33]
	v_readlane_b32 s80, v254, 54
	v_readlane_b32 s82, v254, 56
	v_readlane_b32 s69, v253, 20
	v_readlane_b32 s70, v253, 21
	v_readlane_b32 s71, v253, 22
	v_readlane_b32 s76, v253, 27
	v_readlane_b32 s77, v253, 28
	v_mfma_f32_32x32x16_bf16 v[2:17], v[92:95], v[50:53], v[2:17]
	v_or_b32_e32 v51, 0xdc0, v63
	v_or_b32_e32 v52, v51, v61
	v_lshlrev_b32_e32 v52, 2, v52
	global_load_dword v52, v52, s[0:1]
	v_readlane_b32 s78, v253, 29
	v_readlane_b32 s79, v253, 30
	v_readlane_b32 s81, v254, 55
	v_readlane_b32 s83, v254, 57
	s_waitcnt vmcnt(1)
	v_lshlrev_b32_e32 v46, 16, v42
	v_and_b32_e32 v47, 0xffff0000, v42
	v_lshlrev_b32_e32 v42, 16, v43
	v_and_b32_e32 v43, 0xffff0000, v43
	v_lshlrev_b32_e32 v48, 16, v44
	v_and_b32_e32 v49, 0xffff0000, v44
	v_lshlrev_b32_e32 v44, 16, v45
	v_and_b32_e32 v45, 0xffff0000, v45
	v_pk_fma_f32 v[34:35], v[0:1], v[34:35], v[46:47] op_sel_hi:[0,1,1] neg_lo:[0,0,1] neg_hi:[0,0,1]
	v_pk_fma_f32 v[36:37], v[0:1], v[36:37], v[42:43] op_sel_hi:[0,1,1] neg_lo:[0,0,1] neg_hi:[0,0,1]
	v_pk_fma_f32 v[38:39], v[0:1], v[38:39], v[48:49] op_sel_hi:[0,1,1] neg_lo:[0,0,1] neg_hi:[0,0,1]
	v_pk_fma_f32 v[40:41], v[0:1], v[40:41], v[44:45] op_sel_hi:[0,1,1] neg_lo:[0,0,1] neg_hi:[0,0,1]
	v_or_b32_e32 v0, 0xc00, v63
	v_or_b32_e32 v42, 0xc40, v63
	v_or_b32_e32 v43, 0xc80, v63
	v_or_b32_e32 v44, 0xcc0, v63
	v_or_b32_e32 v45, 0xd00, v63
	v_or_b32_e32 v47, 0xd40, v63
	v_or_b32_e32 v49, 0xd80, v63
	v_cvt_pk_bf16_f32 v34, v34, v35
	v_cvt_pk_bf16_f32 v35, v36, v37
	v_cvt_pk_bf16_f32 v36, v38, v39
	v_cvt_pk_bf16_f32 v37, v40, v41
	v_or_b32_e32 v38, v0, v61
	v_or_b32_e32 v39, v42, v61
	v_or_b32_e32 v40, v43, v61
	v_or_b32_e32 v41, v44, v61
	v_or_b32_e32 v46, v45, v61
	v_or_b32_e32 v48, v47, v61
	v_or_b32_e32 v50, v49, v61
	v_lshlrev_b32_e32 v38, 2, v38
	v_lshlrev_b32_e32 v39, 2, v39
	v_lshlrev_b32_e32 v40, 2, v40
	v_lshlrev_b32_e32 v41, 2, v41
	v_lshlrev_b32_e32 v46, 2, v46
	v_lshlrev_b32_e32 v48, 2, v48
	v_lshlrev_b32_e32 v50, 2, v50
	global_load_dword v38, v38, s[0:1]
	v_or_b32_e32 v0, v0, v62
	global_load_dword v39, v39, s[0:1]
	v_lshlrev_b32_e32 v0, 2, v0
	global_load_dword v40, v40, s[0:1]
	s_nop 0
	global_load_dword v41, v41, s[0:1]
	s_nop 0
	global_load_dword v46, v46, s[0:1]
	s_nop 0
	global_load_dword v48, v48, s[0:1]
	s_nop 0
	global_load_dword v50, v50, s[0:1]
	s_nop 0
	global_load_dword v0, v0, s[0:1]
	s_waitcnt vmcnt(6)
	v_cvt_pk_bf16_f32 v38, v38, v39
	s_waitcnt vmcnt(4)
	v_cvt_pk_bf16_f32 v39, v40, v41
	s_waitcnt vmcnt(2)
	v_cvt_pk_bf16_f32 v40, v46, v48
	s_waitcnt vmcnt(1)
	v_cvt_pk_bf16_f32 v41, v50, v52
	s_nop 1
	v_mfma_f32_32x32x16_bf16 v[18:33], v[38:41], v[34:37], v[18:33]
	v_or_b32_e32 v38, v42, v62
	v_or_b32_e32 v39, v43, v62
	v_or_b32_e32 v40, v44, v62
	v_or_b32_e32 v41, v45, v62
	v_or_b32_e32 v42, v47, v62
	v_or_b32_e32 v43, v49, v62
	v_or_b32_e32 v44, v51, v62
	v_lshlrev_b32_e32 v38, 2, v38
	v_lshlrev_b32_e32 v39, 2, v39
	v_lshlrev_b32_e32 v40, 2, v40
	v_lshlrev_b32_e32 v41, 2, v41
	v_lshlrev_b32_e32 v42, 2, v42
	v_lshlrev_b32_e32 v43, 2, v43
	v_lshlrev_b32_e32 v44, 2, v44
	global_load_dword v38, v38, s[0:1]
	s_nop 0
	global_load_dword v39, v39, s[0:1]
	s_nop 0
	global_load_dword v40, v40, s[0:1]
	s_nop 0
	global_load_dword v41, v41, s[0:1]
	s_nop 0
	global_load_dword v42, v42, s[0:1]
	s_nop 0
	global_load_dword v43, v43, s[0:1]
	s_nop 0
	global_load_dword v44, v44, s[0:1]
	v_readlane_b32 s0, v255, 10
	s_or_b32 s0, s6, s0
	s_waitcnt vmcnt(6)
	v_cvt_pk_bf16_f32 v38, v0, v38
	v_lshl_or_b32 v0, v60, 2, s0
	s_mov_b64 s[0:1], 0x15c00600
	s_waitcnt vmcnt(4)
	v_cvt_pk_bf16_f32 v39, v39, v40
	s_waitcnt vmcnt(2)
	v_cvt_pk_bf16_f32 v40, v41, v42
	s_waitcnt vmcnt(0)
	v_cvt_pk_bf16_f32 v41, v43, v44
	s_nop 1
	v_mfma_f32_32x32x16_bf16 v[2:17], v[38:41], v[34:37], v[2:17]
	v_lshl_add_u64 v[38:39], v[0:1], 2, s[74:75]
	global_load_dwordx4 v[34:37], v[38:39], off
	s_mov_b64 s[74:75], s[26:27]
	v_lshlrev_b32_e32 v0, 3, v60
	s_mov_b64 s[72:73], s[24:25]
	s_waitcnt vmcnt(0)
	v_pk_mul_f32 v[18:19], v[18:19], v[34:35]
	v_pk_mul_f32 v[20:21], v[20:21], v[36:37]
	global_load_dwordx4 v[34:37], v[38:39], off offset:32
	s_waitcnt vmcnt(0)
	v_pk_mul_f32 v[22:23], v[22:23], v[34:35]
	v_pk_mul_f32 v[24:25], v[24:25], v[36:37]
	global_load_dwordx4 v[34:37], v[38:39], off offset:64
	s_waitcnt vmcnt(0)
	v_pk_mul_f32 v[26:27], v[26:27], v[34:35]
	v_pk_mul_f32 v[28:29], v[28:29], v[36:37]
	global_load_dwordx4 v[34:37], v[38:39], off offset:96
	s_waitcnt vmcnt(0)
	v_pk_mul_f32 v[30:31], v[30:31], v[34:35]
	v_pk_mul_f32 v[32:33], v[32:33], v[36:37]
	global_load_dwordx4 v[34:37], v[38:39], off offset:128
	s_waitcnt vmcnt(0)
	v_pk_mul_f32 v[2:3], v[2:3], v[34:35]
	v_pk_mul_f32 v[4:5], v[4:5], v[36:37]
	global_load_dwordx4 v[34:37], v[38:39], off offset:160
	v_cvt_pk_bf16_f32 v2, v2, v3
	v_cvt_pk_bf16_f32 v3, v4, v5
	s_waitcnt vmcnt(0)
	v_pk_mul_f32 v[6:7], v[6:7], v[34:35]
	v_pk_mul_f32 v[8:9], v[8:9], v[36:37]
	global_load_dwordx4 v[34:37], v[38:39], off offset:192
	s_waitcnt vmcnt(0)
	v_pk_mul_f32 v[10:11], v[10:11], v[34:35]
	v_pk_mul_f32 v[12:13], v[12:13], v[36:37]
	global_load_dwordx4 v[34:37], v[38:39], off offset:224
	s_waitcnt vmcnt(0)
	v_pk_mul_f32 v[62:63], v[14:15], v[34:35]
	v_lshlrev_b64 v[14:15], 11, v[54:55]
	v_lshl_add_u64 v[14:15], s[74:75], 0, v[14:15]
	v_lshl_add_u64 v[14:15], v[14:15], 0, s[20:21]
	v_lshl_add_u64 v[14:15], v[14:15], 0, v[0:1]
	v_pk_mul_f32 v[64:65], v[16:17], v[36:37]
	v_lshl_add_u64 v[36:37], v[14:15], 0, s[0:1]
	s_mov_b32 s0, 0x15c00000
	v_add_co_u32_e32 v14, vcc, s0, v14
	v_cvt_pk_bf16_f32 v16, v18, v19
	v_cvt_pk_bf16_f32 v17, v20, v21
	v_addc_co_u32_e32 v15, vcc, 0, v15, vcc
	global_store_dwordx2 v[14:15], v[16:17], off offset:1536
	v_cvt_pk_bf16_f32 v14, v22, v23
	v_cvt_pk_bf16_f32 v15, v24, v25
	global_store_dwordx2 v[36:37], v[14:15], off offset:16
	v_cvt_pk_bf16_f32 v14, v26, v27
	v_cvt_pk_bf16_f32 v15, v28, v29
	global_store_dwordx2 v[36:37], v[2:3], off offset:64
	v_cvt_pk_bf16_f32 v2, v6, v7
	v_cvt_pk_bf16_f32 v3, v8, v9
	global_store_dwordx2 v[36:37], v[14:15], off offset:32
	v_cvt_pk_bf16_f32 v14, v30, v31
	v_cvt_pk_bf16_f32 v15, v32, v33
	global_store_dwordx2 v[36:37], v[2:3], off offset:80
	v_cvt_pk_bf16_f32 v2, v10, v11
	v_cvt_pk_bf16_f32 v3, v12, v13
	global_store_dwordx2 v[36:37], v[14:15], off offset:48
	global_store_dwordx2 v[36:37], v[2:3], off offset:96
	s_mov_b64 s[0:1], 0
